# band mixer-A epilogue: the four z row-group loads issued together (one exposed latency), on top of the simplified diff DMA issue
# speedup vs baseline: 1.0154x; 1.0001x over previous
; DI unsigned pk2(float lo, float hi) { fl2_t f = {lo, hi}; bf2_t b = __builtin_convertvector(f, bf2_t); return __builtin_bit_cast(unsigned, b); }
; DI float bflo(unsigned u) { return __uint_as_float(u << 16); }
; DI float bfhi(unsigned u) { return __uint_as_float(u & 0xffff0000u); }
; DI float silu_f(float z) { return z / (1.f + __expf(-z)); }
; DI void band_item(const Params& P, char* lds_blk, int layer, int bp) {
;     ...
;     const int ch = lane & 7;
; #pragma unroll
;     for (int j = 0; j < 4; ++j) {
;         const int rl = (lane >> 3) + 8 * j;
;         const f32x4 a = *(const f32x4*)(sO + rl * OP + ch * 32), b = *(const f32x4*)(sO + rl * OP + ch * 32 + 16);
;         const size_t orow = base_row + (size_t)(32 * w + rl) * dil;
;         if (type == 0) {
;             const u32x4 zz = *(const u32x4*)(Ph + orow * PO + OFF_Z + head * 64 + ch * 8);
;             u32x4 o = {pk2(a.x * silu_f(bflo(zz.x)), a.y * silu_f(bfhi(zz.x))), pk2(a.z * silu_f(bflo(zz.y)), a.w * silu_f(bfhi(zz.y))),
;                        pk2(b.x * silu_f(bflo(zz.z)), b.y * silu_f(bfhi(zz.z))), pk2(b.z * silu_f(bflo(zz.w)), b.w * silu_f(bfhi(zz.w)))};
;             *(u32x4*)(Ph + orow * PO + OFF_AQ + head * 64 + ch * 8) = o;
.LBB0_228:
	v_ashrrev_i32_e32 v107, 31, v106
	s_andn2_b64 vcc, exec, s[0:1]
	v_lshlrev_b32_e32 v14, 1, v110
	s_cbranch_vccnz .LBB0_230
	v_mov_b64_e32 v[6:7], s[34:35]
	v_mad_u64_u32 v[18:19], s[0:1], v0, s52, v[6:7]
	v_lshl_add_u64 v[6:7], v[106:107], 1, v[18:19]
	v_mov_b32_e32 v15, v1
	v_lshl_add_u64 v[6:7], v[6:7], 0, v[14:15]
	v_add_co_u32_e32 v6, vcc, 0x2000, v6
	s_nop 1
	v_addc_co_u32_e32 v7, vcc, 0, v7, vcc
	global_load_dwordx4 v[238:241], v[6:7], off offset:1792
	s_lshl_b32 s22, s52, 3
	s_lshl_b32 s22, s22, s50
	s_mov_b32 s23, 0
	v_lshl_add_u64 v[6:7], v[6:7], 0, s[22:23]
	global_load_dwordx4 v[242:245], v[6:7], off offset:1792
	v_lshl_add_u64 v[6:7], v[6:7], 0, s[22:23]
	global_load_dwordx4 v[246:249], v[6:7], off offset:1792
	v_lshl_add_u64 v[6:7], v[6:7], 0, s[22:23]
	global_load_dwordx4 v[250:253], v[6:7], off offset:1792
	s_waitcnt vmcnt(0) lgkmcnt(0)
	v_mov_b32_e32 v6, v238
	v_mov_b32_e32 v7, v239
	v_mov_b32_e32 v8, v240
	v_mov_b32_e32 v9, v241
	v_lshlrev_b32_e32 v0, 16, v6
	v_and_b32_e32 v6, 0xffff0000, v6
	v_mul_f32_e32 v15, 0xbfb8aa3b, v0
	v_exp_f32_e32 v22, v15
	v_mul_f32_e32 v15, 0xbfb8aa3b, v6
	v_exp_f32_e32 v23, v15
	s_nop 0
	v_pk_add_f32 v[22:23], v[22:23], 1.0 op_sel_hi:[1,0]
	s_nop 0
	v_div_scale_f32 v15, s[0:1], v23, v23, v6
	v_rcp_f32_e32 v24, v15
	s_nop 0
	v_fma_f32 v25, -v15, v24, 1.0
	v_fmac_f32_e32 v24, v25, v24
	v_div_scale_f32 v25, vcc, v6, v23, v6
	v_mul_f32_e32 v26, v25, v24
	v_fma_f32 v27, -v15, v26, v25
	v_fmac_f32_e32 v26, v27, v24
	v_fma_f32 v15, -v15, v26, v25
	v_div_fmas_f32 v15, v15, v24, v26
	v_div_fixup_f32 v23, v15, v23, v6
	v_div_scale_f32 v6, s[0:1], v22, v22, v0
	v_rcp_f32_e32 v15, v6
	s_nop 0
	v_fma_f32 v24, -v6, v15, 1.0
	v_fmac_f32_e32 v15, v24, v15
	v_div_scale_f32 v24, vcc, v0, v22, v0
	v_mul_f32_e32 v25, v24, v15
	v_fma_f32 v26, -v6, v25, v24
	v_fmac_f32_e32 v25, v26, v15
	v_fma_f32 v6, -v6, v25, v24
	v_div_fmas_f32 v6, v6, v15, v25
	v_div_fixup_f32 v22, v6, v22, v0
	v_pk_mul_f32 v[10:11], v[10:11], v[22:23]
	v_lshlrev_b32_e32 v0, 16, v7
	v_and_b32_e32 v7, 0xffff0000, v7
	v_cvt_pk_bf16_f32 v6, v10, v11
	v_mul_f32_e32 v10, 0xbfb8aa3b, v0
	v_mul_f32_e32 v11, 0xbfb8aa3b, v7
	v_exp_f32_e32 v10, v10
	v_exp_f32_e32 v11, v11
	s_nop 0
	v_pk_add_f32 v[10:11], v[10:11], 1.0 op_sel_hi:[1,0]
	s_nop 0
	v_div_scale_f32 v15, s[0:1], v11, v11, v7
	v_rcp_f32_e32 v22, v15
	s_nop 0
	v_fma_f32 v23, -v15, v22, 1.0
	v_fmac_f32_e32 v22, v23, v22
	v_div_scale_f32 v23, vcc, v7, v11, v7
	v_mul_f32_e32 v24, v23, v22
	v_fma_f32 v25, -v15, v24, v23
	v_fmac_f32_e32 v24, v25, v22
	v_fma_f32 v15, -v15, v24, v23
	v_div_fmas_f32 v15, v15, v22, v24
	v_div_fixup_f32 v11, v15, v11, v7
	v_div_scale_f32 v7, s[0:1], v10, v10, v0
	v_rcp_f32_e32 v15, v7
	s_nop 0
	v_fma_f32 v22, -v7, v15, 1.0
	v_fmac_f32_e32 v15, v22, v15
	v_div_scale_f32 v22, vcc, v0, v10, v0
	v_mul_f32_e32 v23, v22, v15
	v_fma_f32 v24, -v7, v23, v22
	v_fmac_f32_e32 v23, v24, v15
	v_fma_f32 v7, -v7, v23, v22
	v_div_fmas_f32 v7, v7, v15, v23
	v_div_fixup_f32 v10, v7, v10, v0
	v_pk_mul_f32 v[10:11], v[12:13], v[10:11]
	v_lshlrev_b32_e32 v0, 16, v8
	v_and_b32_e32 v8, 0xffff0000, v8
	v_cvt_pk_bf16_f32 v7, v10, v11
	v_mul_f32_e32 v10, 0xbfb8aa3b, v0
	v_mul_f32_e32 v11, 0xbfb8aa3b, v8
	v_exp_f32_e32 v10, v10
	v_exp_f32_e32 v11, v11
	s_nop 0
	v_pk_add_f32 v[10:11], v[10:11], 1.0 op_sel_hi:[1,0]
	s_nop 0
	v_div_scale_f32 v12, s[0:1], v11, v11, v8
	v_rcp_f32_e32 v13, v12
	s_nop 0
	v_fma_f32 v15, -v12, v13, 1.0
	v_fmac_f32_e32 v13, v15, v13
	v_div_scale_f32 v15, vcc, v8, v11, v8
	v_mul_f32_e32 v22, v15, v13
	v_fma_f32 v23, -v12, v22, v15
	v_fmac_f32_e32 v22, v23, v13
	v_fma_f32 v12, -v12, v22, v15
	v_div_fmas_f32 v12, v12, v13, v22
	v_div_fixup_f32 v11, v12, v11, v8
	v_div_scale_f32 v8, s[0:1], v10, v10, v0
	v_rcp_f32_e32 v12, v8
	s_nop 0
	v_fma_f32 v13, -v8, v12, 1.0
	v_fmac_f32_e32 v12, v13, v12
	v_div_scale_f32 v13, vcc, v0, v10, v0
	v_mul_f32_e32 v15, v13, v12
	v_fma_f32 v22, -v8, v15, v13
	v_fmac_f32_e32 v15, v22, v12
	v_fma_f32 v8, -v8, v15, v13
	v_div_fmas_f32 v8, v8, v12, v15
	v_div_fixup_f32 v10, v8, v10, v0
	v_pk_mul_f32 v[2:3], v[2:3], v[10:11]
	v_lshlrev_b32_e32 v0, 16, v9
	v_and_b32_e32 v9, 0xffff0000, v9
	v_cvt_pk_bf16_f32 v8, v2, v3
	v_mul_f32_e32 v2, 0xbfb8aa3b, v0
	v_mul_f32_e32 v3, 0xbfb8aa3b, v9
	v_exp_f32_e32 v2, v2
	v_exp_f32_e32 v3, v3
	s_nop 0
	v_pk_add_f32 v[2:3], v[2:3], 1.0 op_sel_hi:[1,0]
	s_nop 0
	v_div_scale_f32 v10, s[0:1], v3, v3, v9
	v_rcp_f32_e32 v11, v10
	s_nop 0
	v_fma_f32 v12, -v10, v11, 1.0
	v_fmac_f32_e32 v11, v12, v11
	v_div_scale_f32 v12, vcc, v9, v3, v9
	v_mul_f32_e32 v13, v12, v11
	v_fma_f32 v15, -v10, v13, v12
	v_fmac_f32_e32 v13, v15, v11
	v_fma_f32 v10, -v10, v13, v12
	v_div_fmas_f32 v10, v10, v11, v13
	v_div_fixup_f32 v3, v10, v3, v9
	v_div_scale_f32 v9, s[0:1], v2, v2, v0
	v_rcp_f32_e32 v10, v9
	s_nop 0
	v_fma_f32 v11, -v9, v10, 1.0
	v_fmac_f32_e32 v10, v11, v10
	v_div_scale_f32 v11, vcc, v0, v2, v0
	v_mul_f32_e32 v12, v11, v10
	v_fma_f32 v13, -v9, v12, v11
	v_fmac_f32_e32 v12, v13, v10
	v_fma_f32 v9, -v9, v12, v11
	v_div_fmas_f32 v9, v9, v10, v12
	v_div_fixup_f32 v2, v9, v2, v0
	v_pk_mul_f32 v[2:3], v[4:5], v[2:3]
	s_nop 0
	v_cvt_pk_bf16_f32 v9, v2, v3

; DI unsigned pk2(float lo, float hi) { fl2_t f = {lo, hi}; bf2_t b = __builtin_convertvector(f, bf2_t); return __builtin_bit_cast(unsigned, b); }
; DI float bflo(unsigned u) { return __uint_as_float(u << 16); }
; DI float bfhi(unsigned u) { return __uint_as_float(u & 0xffff0000u); }
; DI float silu_f(float z) { return z / (1.f + __expf(-z)); }
; DI void band_item(const Params& P, char* lds_blk, int layer, int bp) {
;     ...
;         const int rl = (lane >> 3) + 8 * j;
;         const f32x4 a = *(const f32x4*)(sO + rl * OP + ch * 32), b = *(const f32x4*)(sO + rl * OP + ch * 32 + 16);
;         const size_t orow = base_row + (size_t)(32 * w + rl) * dil;
;         if (type == 0) {
;             const u32x4 zz = *(const u32x4*)(Ph + orow * PO + OFF_Z + head * 64 + ch * 8);
;             u32x4 o = {pk2(a.x * silu_f(bflo(zz.x)), a.y * silu_f(bfhi(zz.x))), pk2(a.z * silu_f(bflo(zz.y)), a.w * silu_f(bfhi(zz.y))),
;                        pk2(b.x * silu_f(bflo(zz.z)), b.y * silu_f(bfhi(zz.z))), pk2(b.z * silu_f(bflo(zz.w)), b.w * silu_f(bfhi(zz.w)))};
;             *(u32x4*)(Ph + orow * PO + OFF_AQ + head * 64 + ch * 8) = o;
.LBB0_232:
	s_andn2_b64 vcc, exec, s[22:23]
	s_cbranch_vccnz .LBB0_234
	v_mov_b64_e32 v[6:7], s[34:35]
	v_mad_u64_u32 v[18:19], s[22:23], v0, s52, v[6:7]
	s_waitcnt lgkmcnt(0)
	v_mov_b32_e32 v6, v242
	v_mov_b32_e32 v7, v243
	v_mov_b32_e32 v8, v244
	v_mov_b32_e32 v9, v245
	v_lshlrev_b32_e32 v0, 16, v6
	v_and_b32_e32 v6, 0xffff0000, v6
	v_mul_f32_e32 v15, 0xbfb8aa3b, v0
	v_exp_f32_e32 v22, v15
	v_mul_f32_e32 v15, 0xbfb8aa3b, v6
	v_exp_f32_e32 v23, v15
	s_nop 0
	v_pk_add_f32 v[22:23], v[22:23], 1.0 op_sel_hi:[1,0]
	s_nop 0
	v_div_scale_f32 v15, s[22:23], v23, v23, v6
	v_rcp_f32_e32 v24, v15
	s_nop 0
	v_fma_f32 v25, -v15, v24, 1.0
	v_fmac_f32_e32 v24, v25, v24
	v_div_scale_f32 v25, vcc, v6, v23, v6
	v_mul_f32_e32 v26, v25, v24
	v_fma_f32 v27, -v15, v26, v25
	v_fmac_f32_e32 v26, v27, v24
	v_fma_f32 v15, -v15, v26, v25
	v_div_fmas_f32 v15, v15, v24, v26
	v_div_fixup_f32 v23, v15, v23, v6
	v_div_scale_f32 v6, s[22:23], v22, v22, v0
	v_rcp_f32_e32 v15, v6
	s_nop 0
	v_fma_f32 v24, -v6, v15, 1.0
	v_fmac_f32_e32 v15, v24, v15
	v_div_scale_f32 v24, vcc, v0, v22, v0
	v_mul_f32_e32 v25, v24, v15
	v_fma_f32 v26, -v6, v25, v24
	v_fmac_f32_e32 v25, v26, v15
	v_fma_f32 v6, -v6, v25, v24
	v_div_fmas_f32 v6, v6, v15, v25
	v_div_fixup_f32 v22, v6, v22, v0
	v_pk_mul_f32 v[10:11], v[10:11], v[22:23]
	v_lshlrev_b32_e32 v0, 16, v7
	v_and_b32_e32 v7, 0xffff0000, v7
	v_cvt_pk_bf16_f32 v6, v10, v11
	v_mul_f32_e32 v10, 0xbfb8aa3b, v0
	v_mul_f32_e32 v11, 0xbfb8aa3b, v7
	v_exp_f32_e32 v10, v10
	v_exp_f32_e32 v11, v11
	s_nop 0
	v_pk_add_f32 v[10:11], v[10:11], 1.0 op_sel_hi:[1,0]
	s_nop 0
	v_div_scale_f32 v15, s[22:23], v11, v11, v7
	v_rcp_f32_e32 v22, v15
	s_nop 0
	v_fma_f32 v23, -v15, v22, 1.0
	v_fmac_f32_e32 v22, v23, v22
	v_div_scale_f32 v23, vcc, v7, v11, v7
	v_mul_f32_e32 v24, v23, v22
	v_fma_f32 v25, -v15, v24, v23
	v_fmac_f32_e32 v24, v25, v22
	v_fma_f32 v15, -v15, v24, v23
	v_div_fmas_f32 v15, v15, v22, v24
	v_div_fixup_f32 v11, v15, v11, v7
	v_div_scale_f32 v7, s[22:23], v10, v10, v0
	v_rcp_f32_e32 v15, v7
	s_nop 0
	v_fma_f32 v22, -v7, v15, 1.0
	v_fmac_f32_e32 v15, v22, v15
	v_div_scale_f32 v22, vcc, v0, v10, v0
	v_mul_f32_e32 v23, v22, v15
	v_fma_f32 v24, -v7, v23, v22
	v_fmac_f32_e32 v23, v24, v15
	v_fma_f32 v7, -v7, v23, v22
	v_div_fmas_f32 v7, v7, v15, v23
	v_div_fixup_f32 v10, v7, v10, v0
	v_pk_mul_f32 v[10:11], v[12:13], v[10:11]
	v_lshlrev_b32_e32 v0, 16, v8
	v_and_b32_e32 v8, 0xffff0000, v8
	v_cvt_pk_bf16_f32 v7, v10, v11
	v_mul_f32_e32 v10, 0xbfb8aa3b, v0
	v_mul_f32_e32 v11, 0xbfb8aa3b, v8
	v_exp_f32_e32 v10, v10
	v_exp_f32_e32 v11, v11
	s_nop 0
	v_pk_add_f32 v[10:11], v[10:11], 1.0 op_sel_hi:[1,0]
	s_nop 0
	v_div_scale_f32 v12, s[22:23], v11, v11, v8
	v_rcp_f32_e32 v13, v12
	s_nop 0
	v_fma_f32 v15, -v12, v13, 1.0
	v_fmac_f32_e32 v13, v15, v13
	v_div_scale_f32 v15, vcc, v8, v11, v8
	v_mul_f32_e32 v22, v15, v13
	v_fma_f32 v23, -v12, v22, v15
	v_fmac_f32_e32 v22, v23, v13
	v_fma_f32 v12, -v12, v22, v15
	v_div_fmas_f32 v12, v12, v13, v22
	v_div_fixup_f32 v11, v12, v11, v8
	v_div_scale_f32 v8, s[22:23], v10, v10, v0
	v_rcp_f32_e32 v12, v8
	s_nop 0
	v_fma_f32 v13, -v8, v12, 1.0
	v_fmac_f32_e32 v12, v13, v12
	v_div_scale_f32 v13, vcc, v0, v10, v0
	v_mul_f32_e32 v15, v13, v12
	v_fma_f32 v22, -v8, v15, v13
	v_fmac_f32_e32 v15, v22, v12
	v_fma_f32 v8, -v8, v15, v13
	v_div_fmas_f32 v8, v8, v12, v15
	v_div_fixup_f32 v10, v8, v10, v0
	v_pk_mul_f32 v[2:3], v[2:3], v[10:11]
	v_lshlrev_b32_e32 v0, 16, v9
	v_and_b32_e32 v9, 0xffff0000, v9
	v_cvt_pk_bf16_f32 v8, v2, v3
	v_mul_f32_e32 v2, 0xbfb8aa3b, v0
	v_mul_f32_e32 v3, 0xbfb8aa3b, v9
	v_exp_f32_e32 v2, v2
	v_exp_f32_e32 v3, v3
	s_nop 0
	v_pk_add_f32 v[2:3], v[2:3], 1.0 op_sel_hi:[1,0]
	s_nop 0
	v_div_scale_f32 v10, s[22:23], v3, v3, v9
	v_rcp_f32_e32 v11, v10
	s_nop 0
	v_fma_f32 v12, -v10, v11, 1.0
	v_fmac_f32_e32 v11, v12, v11
	v_div_scale_f32 v12, vcc, v9, v3, v9
	v_mul_f32_e32 v13, v12, v11
	v_fma_f32 v15, -v10, v13, v12
	v_fmac_f32_e32 v13, v15, v11
	v_fma_f32 v10, -v10, v13, v12
	v_div_fmas_f32 v10, v10, v11, v13
	v_div_fixup_f32 v3, v10, v3, v9
	v_div_scale_f32 v9, s[22:23], v2, v2, v0
	v_rcp_f32_e32 v10, v9
	s_nop 0
	v_fma_f32 v11, -v9, v10, 1.0
	v_fmac_f32_e32 v10, v11, v10
	v_div_scale_f32 v11, vcc, v0, v2, v0
	v_mul_f32_e32 v12, v11, v10
	v_fma_f32 v13, -v9, v12, v11
	v_fmac_f32_e32 v12, v13, v10
	v_fma_f32 v9, -v9, v12, v11
	v_div_fmas_f32 v9, v9, v10, v12
	v_div_fixup_f32 v2, v9, v2, v0
	v_pk_mul_f32 v[2:3], v[4:5], v[2:3]
	s_nop 0
	v_cvt_pk_bf16_f32 v9, v2, v3

; DI unsigned pk2(float lo, float hi) { fl2_t f = {lo, hi}; bf2_t b = __builtin_convertvector(f, bf2_t); return __builtin_bit_cast(unsigned, b); }
; DI float bflo(unsigned u) { return __uint_as_float(u << 16); }
; DI float bfhi(unsigned u) { return __uint_as_float(u & 0xffff0000u); }
; DI float silu_f(float z) { return z / (1.f + __expf(-z)); }
; DI void band_item(const Params& P, char* lds_blk, int layer, int bp) {
;     ...
;         const int rl = (lane >> 3) + 8 * j;
;         const f32x4 a = *(const f32x4*)(sO + rl * OP + ch * 32), b = *(const f32x4*)(sO + rl * OP + ch * 32 + 16);
;         const size_t orow = base_row + (size_t)(32 * w + rl) * dil;
;         if (type == 0) {
;             const u32x4 zz = *(const u32x4*)(Ph + orow * PO + OFF_Z + head * 64 + ch * 8);
;             u32x4 o = {pk2(a.x * silu_f(bflo(zz.x)), a.y * silu_f(bfhi(zz.x))), pk2(a.z * silu_f(bflo(zz.y)), a.w * silu_f(bfhi(zz.y))),
;                        pk2(b.x * silu_f(bflo(zz.z)), b.y * silu_f(bfhi(zz.z))), pk2(b.z * silu_f(bflo(zz.w)), b.w * silu_f(bfhi(zz.w)))};
;             *(u32x4*)(Ph + orow * PO + OFF_AQ + head * 64 + ch * 8) = o;
.LBB0_236:
	s_andn2_b64 vcc, exec, s[22:23]
	s_cbranch_vccnz .LBB0_238
	v_mov_b64_e32 v[6:7], s[34:35]
	v_mad_u64_u32 v[18:19], s[22:23], v0, s52, v[6:7]
	s_waitcnt lgkmcnt(0)
	v_mov_b32_e32 v6, v246
	v_mov_b32_e32 v7, v247
	v_mov_b32_e32 v8, v248
	v_mov_b32_e32 v9, v249
	v_lshlrev_b32_e32 v0, 16, v6
	v_and_b32_e32 v6, 0xffff0000, v6
	v_mul_f32_e32 v15, 0xbfb8aa3b, v0
	v_exp_f32_e32 v22, v15
	v_mul_f32_e32 v15, 0xbfb8aa3b, v6
	v_exp_f32_e32 v23, v15
	s_nop 0
	v_pk_add_f32 v[22:23], v[22:23], 1.0 op_sel_hi:[1,0]
	s_nop 0
	v_div_scale_f32 v15, s[22:23], v23, v23, v6
	v_rcp_f32_e32 v24, v15
	s_nop 0
	v_fma_f32 v25, -v15, v24, 1.0
	v_fmac_f32_e32 v24, v25, v24
	v_div_scale_f32 v25, vcc, v6, v23, v6
	v_mul_f32_e32 v26, v25, v24
	v_fma_f32 v27, -v15, v26, v25
	v_fmac_f32_e32 v26, v27, v24
	v_fma_f32 v15, -v15, v26, v25
	v_div_fmas_f32 v15, v15, v24, v26
	v_div_fixup_f32 v23, v15, v23, v6
	v_div_scale_f32 v6, s[22:23], v22, v22, v0
	v_rcp_f32_e32 v15, v6
	s_nop 0
	v_fma_f32 v24, -v6, v15, 1.0
	v_fmac_f32_e32 v15, v24, v15
	v_div_scale_f32 v24, vcc, v0, v22, v0
	v_mul_f32_e32 v25, v24, v15
	v_fma_f32 v26, -v6, v25, v24
	v_fmac_f32_e32 v25, v26, v15
	v_fma_f32 v6, -v6, v25, v24
	v_div_fmas_f32 v6, v6, v15, v25
	v_div_fixup_f32 v22, v6, v22, v0
	v_pk_mul_f32 v[10:11], v[10:11], v[22:23]
	v_lshlrev_b32_e32 v0, 16, v7
	v_and_b32_e32 v7, 0xffff0000, v7
	v_cvt_pk_bf16_f32 v6, v10, v11
	v_mul_f32_e32 v10, 0xbfb8aa3b, v0
	v_mul_f32_e32 v11, 0xbfb8aa3b, v7
	v_exp_f32_e32 v10, v10
	v_exp_f32_e32 v11, v11
	s_nop 0
	v_pk_add_f32 v[10:11], v[10:11], 1.0 op_sel_hi:[1,0]
	s_nop 0
	v_div_scale_f32 v15, s[22:23], v11, v11, v7
	v_rcp_f32_e32 v22, v15
	s_nop 0
	v_fma_f32 v23, -v15, v22, 1.0
	v_fmac_f32_e32 v22, v23, v22
	v_div_scale_f32 v23, vcc, v7, v11, v7
	v_mul_f32_e32 v24, v23, v22
	v_fma_f32 v25, -v15, v24, v23
	v_fmac_f32_e32 v24, v25, v22
	v_fma_f32 v15, -v15, v24, v23
	v_div_fmas_f32 v15, v15, v22, v24
	v_div_fixup_f32 v11, v15, v11, v7
	v_div_scale_f32 v7, s[22:23], v10, v10, v0
	v_rcp_f32_e32 v15, v7
	s_nop 0
	v_fma_f32 v22, -v7, v15, 1.0
	v_fmac_f32_e32 v15, v22, v15
	v_div_scale_f32 v22, vcc, v0, v10, v0
	v_mul_f32_e32 v23, v22, v15
	v_fma_f32 v24, -v7, v23, v22
	v_fmac_f32_e32 v23, v24, v15
	v_fma_f32 v7, -v7, v23, v22
	v_div_fmas_f32 v7, v7, v15, v23
	v_div_fixup_f32 v10, v7, v10, v0
	v_pk_mul_f32 v[10:11], v[12:13], v[10:11]
	v_lshlrev_b32_e32 v0, 16, v8
	v_and_b32_e32 v8, 0xffff0000, v8
	v_cvt_pk_bf16_f32 v7, v10, v11
	v_mul_f32_e32 v10, 0xbfb8aa3b, v0
	v_mul_f32_e32 v11, 0xbfb8aa3b, v8
	v_exp_f32_e32 v10, v10
	v_exp_f32_e32 v11, v11
	s_nop 0
	v_pk_add_f32 v[10:11], v[10:11], 1.0 op_sel_hi:[1,0]
	s_nop 0
	v_div_scale_f32 v12, s[22:23], v11, v11, v8
	v_rcp_f32_e32 v13, v12
	s_nop 0
	v_fma_f32 v15, -v12, v13, 1.0
	v_fmac_f32_e32 v13, v15, v13
	v_div_scale_f32 v15, vcc, v8, v11, v8
	v_mul_f32_e32 v22, v15, v13
	v_fma_f32 v23, -v12, v22, v15
	v_fmac_f32_e32 v22, v23, v13
	v_fma_f32 v12, -v12, v22, v15
	v_div_fmas_f32 v12, v12, v13, v22
	v_div_fixup_f32 v11, v12, v11, v8
	v_div_scale_f32 v8, s[22:23], v10, v10, v0
	v_rcp_f32_e32 v12, v8
	s_nop 0
	v_fma_f32 v13, -v8, v12, 1.0
	v_fmac_f32_e32 v12, v13, v12
	v_div_scale_f32 v13, vcc, v0, v10, v0
	v_mul_f32_e32 v15, v13, v12
	v_fma_f32 v22, -v8, v15, v13
	v_fmac_f32_e32 v15, v22, v12
	v_fma_f32 v8, -v8, v15, v13
	v_div_fmas_f32 v8, v8, v12, v15
	v_div_fixup_f32 v10, v8, v10, v0
	v_pk_mul_f32 v[2:3], v[2:3], v[10:11]
	v_lshlrev_b32_e32 v0, 16, v9
	v_and_b32_e32 v9, 0xffff0000, v9
	v_cvt_pk_bf16_f32 v8, v2, v3
	v_mul_f32_e32 v2, 0xbfb8aa3b, v0
	v_mul_f32_e32 v3, 0xbfb8aa3b, v9
	v_exp_f32_e32 v2, v2
	v_exp_f32_e32 v3, v3
	s_nop 0
	v_pk_add_f32 v[2:3], v[2:3], 1.0 op_sel_hi:[1,0]
	s_nop 0
	v_div_scale_f32 v10, s[22:23], v3, v3, v9
	v_rcp_f32_e32 v11, v10
	s_nop 0
	v_fma_f32 v12, -v10, v11, 1.0
	v_fmac_f32_e32 v11, v12, v11
	v_div_scale_f32 v12, vcc, v9, v3, v9
	v_mul_f32_e32 v13, v12, v11
	v_fma_f32 v15, -v10, v13, v12
	v_fmac_f32_e32 v13, v15, v11
	v_fma_f32 v10, -v10, v13, v12
	v_div_fmas_f32 v10, v10, v11, v13
	v_div_fixup_f32 v3, v10, v3, v9
	v_div_scale_f32 v9, s[22:23], v2, v2, v0
	v_rcp_f32_e32 v10, v9
	s_nop 0
	v_fma_f32 v11, -v9, v10, 1.0
	v_fmac_f32_e32 v10, v11, v10
	v_div_scale_f32 v11, vcc, v0, v2, v0
	v_mul_f32_e32 v12, v11, v10
	v_fma_f32 v13, -v9, v12, v11
	v_fmac_f32_e32 v12, v13, v10
	v_fma_f32 v9, -v9, v12, v11
	v_div_fmas_f32 v9, v9, v10, v12
	v_div_fixup_f32 v2, v9, v2, v0
	v_pk_mul_f32 v[2:3], v[4:5], v[2:3]
	s_nop 0
	v_cvt_pk_bf16_f32 v9, v2, v3

; DI unsigned pk2(float lo, float hi) { fl2_t f = {lo, hi}; bf2_t b = __builtin_convertvector(f, bf2_t); return __builtin_bit_cast(unsigned, b); }
; DI float bflo(unsigned u) { return __uint_as_float(u << 16); }
; DI float bfhi(unsigned u) { return __uint_as_float(u & 0xffff0000u); }
; DI float silu_f(float z) { return z / (1.f + __expf(-z)); }
; DI void band_item(const Params& P, char* lds_blk, int layer, int bp) {
;     ...
;         const int rl = (lane >> 3) + 8 * j;
;         const f32x4 a = *(const f32x4*)(sO + rl * OP + ch * 32), b = *(const f32x4*)(sO + rl * OP + ch * 32 + 16);
;         const size_t orow = base_row + (size_t)(32 * w + rl) * dil;
;         if (type == 0) {
;             const u32x4 zz = *(const u32x4*)(Ph + orow * PO + OFF_Z + head * 64 + ch * 8);
;             u32x4 o = {pk2(a.x * silu_f(bflo(zz.x)), a.y * silu_f(bfhi(zz.x))), pk2(a.z * silu_f(bflo(zz.y)), a.w * silu_f(bfhi(zz.y))),
;                        pk2(b.x * silu_f(bflo(zz.z)), b.y * silu_f(bfhi(zz.z))), pk2(b.z * silu_f(bflo(zz.w)), b.w * silu_f(bfhi(zz.w)))};
;             *(u32x4*)(Ph + orow * PO + OFF_AQ + head * 64 + ch * 8) = o;
.LBB0_240:
	s_andn2_b64 vcc, exec, s[0:1]
	s_cbranch_vccnz .LBB0_242
	v_mov_b64_e32 v[6:7], s[34:35]
	v_mad_u64_u32 v[18:19], s[0:1], v0, s52, v[6:7]
	s_waitcnt lgkmcnt(0)
	v_mov_b32_e32 v6, v250
	v_mov_b32_e32 v7, v251
	v_mov_b32_e32 v8, v252
	v_mov_b32_e32 v9, v253
	v_lshlrev_b32_e32 v0, 16, v6
	v_and_b32_e32 v6, 0xffff0000, v6
	v_mul_f32_e32 v15, 0xbfb8aa3b, v0
	v_exp_f32_e32 v16, v15
	v_mul_f32_e32 v15, 0xbfb8aa3b, v6
	v_exp_f32_e32 v17, v15
	s_nop 0
	v_pk_add_f32 v[16:17], v[16:17], 1.0 op_sel_hi:[1,0]
	s_nop 0
	v_div_scale_f32 v15, s[0:1], v17, v17, v6
	v_rcp_f32_e32 v20, v15
	s_nop 0
	v_fma_f32 v21, -v15, v20, 1.0
	v_fmac_f32_e32 v20, v21, v20
	v_div_scale_f32 v21, vcc, v6, v17, v6
	v_mul_f32_e32 v22, v21, v20
	v_fma_f32 v23, -v15, v22, v21
	v_fmac_f32_e32 v22, v23, v20
	v_fma_f32 v15, -v15, v22, v21
	v_div_fmas_f32 v15, v15, v20, v22
	v_div_fixup_f32 v17, v15, v17, v6
	v_div_scale_f32 v6, s[0:1], v16, v16, v0
	v_rcp_f32_e32 v15, v6
	s_nop 0
	v_fma_f32 v20, -v6, v15, 1.0
	v_fmac_f32_e32 v15, v20, v15
	v_div_scale_f32 v20, vcc, v0, v16, v0
	v_mul_f32_e32 v21, v20, v15
	v_fma_f32 v22, -v6, v21, v20
	v_fmac_f32_e32 v21, v22, v15
	v_fma_f32 v6, -v6, v21, v20
	v_div_fmas_f32 v6, v6, v15, v21
	v_div_fixup_f32 v16, v6, v16, v0
	v_pk_mul_f32 v[10:11], v[10:11], v[16:17]
	v_lshlrev_b32_e32 v0, 16, v7
	v_and_b32_e32 v7, 0xffff0000, v7
	v_cvt_pk_bf16_f32 v6, v10, v11
	v_mul_f32_e32 v10, 0xbfb8aa3b, v0
	v_mul_f32_e32 v11, 0xbfb8aa3b, v7
	v_exp_f32_e32 v10, v10
	v_exp_f32_e32 v11, v11
	s_nop 0
	v_pk_add_f32 v[10:11], v[10:11], 1.0 op_sel_hi:[1,0]
	s_nop 0
	v_div_scale_f32 v15, s[0:1], v11, v11, v7
	v_rcp_f32_e32 v16, v15
	s_nop 0
	v_fma_f32 v17, -v15, v16, 1.0
	v_fmac_f32_e32 v16, v17, v16
	v_div_scale_f32 v17, vcc, v7, v11, v7
	v_mul_f32_e32 v20, v17, v16
	v_fma_f32 v21, -v15, v20, v17
	v_fmac_f32_e32 v20, v21, v16
	v_fma_f32 v15, -v15, v20, v17
	v_div_fmas_f32 v15, v15, v16, v20
	v_div_fixup_f32 v11, v15, v11, v7
	v_div_scale_f32 v7, s[0:1], v10, v10, v0
	v_rcp_f32_e32 v15, v7
	s_nop 0
	v_fma_f32 v16, -v7, v15, 1.0
	v_fmac_f32_e32 v15, v16, v15
	v_div_scale_f32 v16, vcc, v0, v10, v0
	v_mul_f32_e32 v17, v16, v15
	v_fma_f32 v20, -v7, v17, v16
	v_fmac_f32_e32 v17, v20, v15
	v_fma_f32 v7, -v7, v17, v16
	v_div_fmas_f32 v7, v7, v15, v17
	v_div_fixup_f32 v10, v7, v10, v0
	v_pk_mul_f32 v[10:11], v[12:13], v[10:11]
	v_lshlrev_b32_e32 v0, 16, v8
	v_and_b32_e32 v8, 0xffff0000, v8
	v_cvt_pk_bf16_f32 v7, v10, v11
	v_mul_f32_e32 v10, 0xbfb8aa3b, v0
	v_mul_f32_e32 v11, 0xbfb8aa3b, v8
	v_exp_f32_e32 v10, v10
	v_exp_f32_e32 v11, v11
	s_nop 0
	v_pk_add_f32 v[10:11], v[10:11], 1.0 op_sel_hi:[1,0]
	s_nop 0
	v_div_scale_f32 v12, s[0:1], v11, v11, v8
	v_rcp_f32_e32 v13, v12
	s_nop 0
	v_fma_f32 v15, -v12, v13, 1.0
	v_fmac_f32_e32 v13, v15, v13
	v_div_scale_f32 v15, vcc, v8, v11, v8
	v_mul_f32_e32 v16, v15, v13
	v_fma_f32 v17, -v12, v16, v15
	v_fmac_f32_e32 v16, v17, v13
	v_fma_f32 v12, -v12, v16, v15
	v_div_fmas_f32 v12, v12, v13, v16
	v_div_fixup_f32 v11, v12, v11, v8
	v_div_scale_f32 v8, s[0:1], v10, v10, v0
	v_rcp_f32_e32 v12, v8
	s_nop 0
	v_fma_f32 v13, -v8, v12, 1.0
	v_fmac_f32_e32 v12, v13, v12
	v_div_scale_f32 v13, vcc, v0, v10, v0
	v_mul_f32_e32 v15, v13, v12
	v_fma_f32 v16, -v8, v15, v13
	v_fmac_f32_e32 v15, v16, v12
	v_fma_f32 v8, -v8, v15, v13
	v_div_fmas_f32 v8, v8, v12, v15
	v_div_fixup_f32 v10, v8, v10, v0
	v_pk_mul_f32 v[2:3], v[2:3], v[10:11]
	v_lshlrev_b32_e32 v0, 16, v9
	v_and_b32_e32 v9, 0xffff0000, v9
	v_cvt_pk_bf16_f32 v8, v2, v3
	v_mul_f32_e32 v2, 0xbfb8aa3b, v0
	v_mul_f32_e32 v3, 0xbfb8aa3b, v9
	v_exp_f32_e32 v2, v2
	v_exp_f32_e32 v3, v3
	s_nop 0
	v_pk_add_f32 v[2:3], v[2:3], 1.0 op_sel_hi:[1,0]
	s_nop 0
	v_div_scale_f32 v10, s[0:1], v3, v3, v9
	v_rcp_f32_e32 v11, v10
	s_nop 0
	v_fma_f32 v12, -v10, v11, 1.0
	v_fmac_f32_e32 v11, v12, v11
	v_div_scale_f32 v12, vcc, v9, v3, v9
	v_mul_f32_e32 v13, v12, v11
	v_fma_f32 v15, -v10, v13, v12
	v_fmac_f32_e32 v13, v15, v11
	v_fma_f32 v10, -v10, v13, v12
	v_div_fmas_f32 v10, v10, v11, v13
	v_div_fixup_f32 v3, v10, v3, v9
	v_div_scale_f32 v9, s[0:1], v2, v2, v0
	v_rcp_f32_e32 v10, v9
	s_nop 0
	v_fma_f32 v11, -v9, v10, 1.0
	v_fmac_f32_e32 v10, v11, v10
	v_div_scale_f32 v11, vcc, v0, v2, v0
	v_mul_f32_e32 v12, v11, v10
	v_fma_f32 v13, -v9, v12, v11
	v_fmac_f32_e32 v12, v13, v10
	v_fma_f32 v9, -v9, v12, v11
	v_div_fmas_f32 v9, v9, v10, v12
	v_div_fixup_f32 v2, v9, v2, v0
	v_pk_mul_f32 v[2:3], v[4:5], v[2:3]
	s_nop 0
	v_cvt_pk_bf16_f32 v9, v2, v3

; __global__ void __launch_bounds__(512, 1) mega(Params P) {
;     extern __shared__ __attribute__((aligned(16))) char lds[];
	.amdhsa_kernel _Z4mega6Params
		.amdhsa_group_segment_fixed_size 0
		.amdhsa_private_segment_fixed_size 0
		.amdhsa_kernarg_size 392
		.amdhsa_user_sgpr_count 2
		.amdhsa_user_sgpr_dispatch_ptr 0
		.amdhsa_user_sgpr_queue_ptr 0
		.amdhsa_user_sgpr_kernarg_segment_ptr 1
		.amdhsa_user_sgpr_dispatch_id 0
		.amdhsa_user_sgpr_kernarg_preload_length 0
		.amdhsa_user_sgpr_kernarg_preload_offset 0
		.amdhsa_user_sgpr_private_segment_size 0
		.amdhsa_uses_dynamic_stack 0
		.amdhsa_enable_private_segment 0
		.amdhsa_system_sgpr_workgroup_id_x 1
		.amdhsa_system_sgpr_workgroup_id_y 0
		.amdhsa_system_sgpr_workgroup_id_z 0
		.amdhsa_system_sgpr_workgroup_info 0
		.amdhsa_system_vgpr_workitem_id 2
		.amdhsa_next_free_vgpr 256
		.amdhsa_next_free_sgpr 100
		.amdhsa_accum_offset 256
		.amdhsa_reserve_vcc 1
		.amdhsa_float_round_mode_32 0
		.amdhsa_float_round_mode_16_64 0
		.amdhsa_float_denorm_mode_32 3
		.amdhsa_float_denorm_mode_16_64 3
		.amdhsa_dx10_clamp 1
		.amdhsa_ieee_mode 1
		.amdhsa_fp16_overflow 0
		.amdhsa_tg_split 0
		.amdhsa_exception_fp_ieee_invalid_op 0
		.amdhsa_exception_fp_denorm_src 0
		.amdhsa_exception_fp_ieee_div_zero 0
		.amdhsa_exception_fp_ieee_overflow 0
		.amdhsa_exception_fp_ieee_underflow 0
		.amdhsa_exception_fp_ieee_inexact 0
		.amdhsa_exception_int_div_zero 0
	.end_amdhsa_kernel

; __global__ void __launch_bounds__(512, 1) mega(Params P) {
;     extern __shared__ __attribute__((aligned(16))) char lds[];
amdhsa.kernels:
  - .agpr_count:     0
    .args:
      - .offset:         0
        .size:           136
        .value_kind:     by_value
      - .offset:         136
        .size:           4
        .value_kind:     hidden_block_count_x
      - .offset:         140
        .size:           4
        .value_kind:     hidden_block_count_y
      - .offset:         144
        .size:           4
        .value_kind:     hidden_block_count_z
      - .offset:         148
        .size:           2
        .value_kind:     hidden_group_size_x
      - .offset:         150
        .size:           2
        .value_kind:     hidden_group_size_y
      - .offset:         152
        .size:           2
        .value_kind:     hidden_group_size_z
      - .offset:         154
        .size:           2
        .value_kind:     hidden_remainder_x
      - .offset:         156
        .size:           2
        .value_kind:     hidden_remainder_y
      - .offset:         158
        .size:           2
        .value_kind:     hidden_remainder_z
      - .offset:         176
        .size:           8
        .value_kind:     hidden_global_offset_x
      - .offset:         184
        .size:           8
        .value_kind:     hidden_global_offset_y
      - .offset:         192
        .size:           8
        .value_kind:     hidden_global_offset_z
      - .offset:         200
        .size:           2
        .value_kind:     hidden_grid_dims
      - .offset:         224
        .size:           8
        .value_kind:     hidden_multigrid_sync_arg
      - .offset:         256
        .size:           4
        .value_kind:     hidden_dynamic_lds_size
    .group_segment_fixed_size: 0
    .kernarg_segment_align: 8
    .kernarg_segment_size: 392
    .language:       OpenCL C
    .language_version:
      - 2
      - 0
    .max_flat_workgroup_size: 512
    .name:           _Z4mega6Params
    .private_segment_fixed_size: 0
    .sgpr_count:     106
    .sgpr_spill_count: 118
    .symbol:         _Z4mega6Params.kd
    .uniform_work_group_size: 1
    .uses_dynamic_stack: false
    .vgpr_count:     256
    .vgpr_spill_count: 0
    .wavefront_size: 64
